# plus: rtab_fill tile decode uses mask instead of generic modulo
# baseline (speedup 1.0000x reference)
.LBB0_109:
	v_cmp_gt_i64_e32 vcc, s[10:11], v[10:11]
	s_mov_b64 s[52:53], -1
	s_cbranch_vccnz .LBB0_108
	s_ashr_i32 s27, s10, 31
	s_lshr_b32 s27, s27, 29
	s_add_i32 s27, s10, s27
	s_ashr_i32 s33, s27, 3
	s_and_b32 s27, s27, -8
	s_sub_i32 s27, s10, s27
	s_cmp_lt_i32 s27, 0
	s_cselect_b32 s52, s24, 0x160
	s_mul_i32 s27, s27, s52
	s_add_i32 s27, s27, s33
	s_mul_hi_i32 s33, s27, 0x2e8ba2e9
	s_lshr_b32 s52, s33, 31
	s_ashr_i32 s33, s33, 4
	s_add_i32 s33, s33, s52
	s_lshl_b32 s52, s33, 2
	s_sub_i32 s53, 0x80, s52
	s_min_i32 s53, s53, 4
	s_mulk_i32 s33, 0x58
	s_sub_i32 s27, s27, s33
	v_cmp_lt_i32_e32 vcc, v19, v173
	s_and_b32 s27, s27, 3
	s_add_i32 s52, s52, s27
	v_cndmask_b32_e32 v28, v172, v19, vcc
	v_lshl_add_u32 v20, s52, 8, v16
	s_waitcnt lgkmcnt(0)
	v_ashrrev_i32_e32 v21, 31, v20
	v_lshlrev_b64 v[20:21], 6, v[20:21]
	v_lshl_add_u64 v[24:25], v[8:9], 0, v[20:21]
	global_load_dwordx4 v[20:23], v[24:25], off
	s_nop 0
	global_load_dwordx4 v[24:27], v[24:25], off offset:16
	s_waitcnt vmcnt(0)
	v_add_f32_e32 v20, v20, v21
	v_add_f32_e32 v21, v22, v23
	v_add_f32_e32 v22, v24, v25
	v_add_f32_e32 v23, v26, v27
	v_add_f32_e32 v20, v20, v21
	v_add_f32_e32 v21, v22, v23
	v_add_f32_e32 v20, v20, v21
	v_lshlrev_b32_e32 v21, 2, v28
	ds_bpermute_b32 v21, v21, v20
	s_and_saveexec_b64 s[52:53], s[6:7]
	s_cbranch_execz .LBB0_107
	s_waitcnt lgkmcnt(0)
	v_add_f32_e32 v20, v20, v21
	v_fmamk_f32 v20, v20, 0x3a800000, v18
	v_rsq_f32_e32 v20, v20
	v_add_u32_e32 v21, s26, v17
	ds_write_b32 v21, v20 offset:14336
	s_branch .LBB0_107

.LBB0_418:
	v_cmp_gt_i64_e32 vcc, s[10:11], v[10:11]
	s_mov_b64 s[52:53], -1
	s_cbranch_vccnz .LBB0_417
	s_ashr_i32 s17, s10, 31
	s_lshr_b32 s17, s17, 29
	s_add_i32 s17, s10, s17
	s_ashr_i32 s18, s17, 3
	s_and_b32 s17, s17, -8
	s_sub_i32 s17, s10, s17
	s_cmp_lt_i32 s17, 0
	s_movk_i32 s19, 0xa1
	s_cselect_b32 s19, s19, 0xa0
	s_mul_i32 s17, s17, s19
	s_add_i32 s17, s17, s18
	s_mul_hi_i32 s18, s17, 0x66666667
	s_lshr_b32 s19, s18, 31
	s_ashr_i32 s18, s18, 4
	s_add_i32 s18, s18, s19
	s_lshl_b32 s19, s18, 2
	s_sub_i32 s20, 0x80, s19
	s_min_i32 s20, s20, 4
	s_mul_i32 s18, s18, 40
	s_sub_i32 s17, s17, s18
	v_cmp_lt_i32_e32 vcc, v19, v155
	s_and_b32 s17, s17, 3
	s_add_i32 s19, s19, s17
	v_cndmask_b32_e32 v28, v149, v19, vcc
	v_lshl_add_u32 v20, s19, 8, v16
	s_waitcnt lgkmcnt(0)
	v_ashrrev_i32_e32 v21, 31, v20
	v_lshlrev_b64 v[20:21], 6, v[20:21]
	v_lshl_add_u64 v[24:25], v[8:9], 0, v[20:21]
	global_load_dwordx4 v[20:23], v[24:25], off
	s_nop 0
	global_load_dwordx4 v[24:27], v[24:25], off offset:16
	s_waitcnt vmcnt(0)
	v_add_f32_e32 v20, v20, v21
	v_add_f32_e32 v21, v22, v23
	v_add_f32_e32 v22, v24, v25
	v_add_f32_e32 v23, v26, v27
	v_add_f32_e32 v20, v20, v21
	v_add_f32_e32 v21, v22, v23
	v_add_f32_e32 v20, v20, v21
	v_lshlrev_b32_e32 v21, 2, v28
	ds_bpermute_b32 v21, v21, v20
	s_and_saveexec_b64 s[52:53], s[8:9]
	s_cbranch_execz .LBB0_416
	s_waitcnt lgkmcnt(0)
	v_add_f32_e32 v20, v20, v21
	v_fmamk_f32 v20, v20, 0x3a800000, v18
	v_rsq_f32_e32 v20, v20
	v_add_u32_e32 v21, s14, v17
	ds_write_b32 v21, v20 offset:14336
	s_branch .LBB0_416

.LBB0_1137:
	v_cmp_gt_i64_e32 vcc, s[8:9], v[10:11]
	s_mov_b64 s[10:11], -1
	s_cbranch_vccnz .LBB0_1136
	s_ashr_i32 s10, s8, 31
	s_lshr_b32 s10, s10, 29
	s_add_i32 s10, s8, s10
	s_ashr_i32 s11, s10, 3
	s_and_b32 s10, s10, -8
	s_sub_i32 s10, s8, s10
	s_cmp_lt_i32 s10, 0
	s_cselect_b32 s27, s24, 0x160
	s_mul_i32 s10, s10, s27
	s_add_i32 s10, s10, s11
	s_mul_hi_i32 s11, s10, 0x2e8ba2e9
	s_lshr_b32 s27, s11, 31
	s_ashr_i32 s11, s11, 4
	s_add_i32 s11, s11, s27
	s_lshl_b32 s27, s11, 2
	s_sub_i32 s33, 0x80, s27
	s_min_i32 s33, s33, 4
	s_mulk_i32 s11, 0x58
	s_sub_i32 s10, s10, s11
	v_cmp_lt_i32_e32 vcc, v19, v169
	s_and_b32 s10, s10, 3
	s_add_i32 s27, s27, s10
	v_cndmask_b32_e32 v28, v168, v19, vcc
	v_lshl_add_u32 v20, s27, 8, v16
	s_waitcnt lgkmcnt(0)
	v_ashrrev_i32_e32 v21, 31, v20
	v_lshlrev_b64 v[20:21], 6, v[20:21]
	v_lshl_add_u64 v[24:25], v[8:9], 0, v[20:21]
	global_load_dwordx4 v[20:23], v[24:25], off
	s_nop 0
	global_load_dwordx4 v[24:27], v[24:25], off offset:16
	s_waitcnt vmcnt(0)
	v_add_f32_e32 v20, v20, v21
	v_add_f32_e32 v21, v22, v23
	v_add_f32_e32 v22, v24, v25
	v_add_f32_e32 v23, v26, v27
	v_add_f32_e32 v20, v20, v21
	v_add_f32_e32 v21, v22, v23
	v_add_f32_e32 v20, v20, v21
	v_lshlrev_b32_e32 v21, 2, v28
	ds_bpermute_b32 v21, v21, v20
	s_and_saveexec_b64 s[10:11], s[4:5]
	s_cbranch_execz .LBB0_1135
	s_waitcnt lgkmcnt(0)
	v_add_f32_e32 v20, v20, v21
	v_fmamk_f32 v20, v20, 0x3a800000, v18
	v_rsq_f32_e32 v20, v20
	v_add_u32_e32 v21, s26, v17
	ds_write_b32 v21, v20 offset:14336
	s_branch .LBB0_1135

.LBB0_1749:
	v_cmp_gt_i64_e32 vcc, s[8:9], v[10:11]
	s_mov_b64 s[10:11], -1
	s_cbranch_vccnz .LBB0_1748
	s_ashr_i32 s10, s8, 31
	s_lshr_b32 s10, s10, 29
	s_add_i32 s10, s8, s10
	s_ashr_i32 s11, s10, 3
	s_and_b32 s10, s10, -8
	s_sub_i32 s10, s8, s10
	s_cmp_lt_i32 s10, 0
	s_cselect_b32 s27, s24, 0xc0
	s_mul_i32 s10, s10, s27
	s_add_i32 s10, s10, s11
	s_mul_hi_i32 s11, s10, 0x2aaaaaab
	s_lshr_b32 s27, s11, 31
	s_ashr_i32 s11, s11, 3
	s_add_i32 s11, s11, s27
	s_lshl_b32 s27, s11, 2
	s_sub_i32 s33, 0x80, s27
	s_min_i32 s33, s33, 4
	s_mul_i32 s11, s11, 48
	s_sub_i32 s10, s10, s11
	v_cmp_lt_i32_e32 vcc, v19, v175
	s_and_b32 s10, s10, 3
	s_add_i32 s27, s27, s10
	v_cndmask_b32_e32 v28, v174, v19, vcc
	v_lshl_add_u32 v20, s27, 8, v16
	s_waitcnt lgkmcnt(0)
	v_ashrrev_i32_e32 v21, 31, v20
	v_lshlrev_b64 v[20:21], 6, v[20:21]
	v_lshl_add_u64 v[24:25], v[8:9], 0, v[20:21]
	global_load_dwordx4 v[20:23], v[24:25], off
	s_nop 0
	global_load_dwordx4 v[24:27], v[24:25], off offset:16
	s_waitcnt vmcnt(0)
	v_add_f32_e32 v20, v20, v21
	v_add_f32_e32 v21, v22, v23
	v_add_f32_e32 v22, v24, v25
	v_add_f32_e32 v23, v26, v27
	v_add_f32_e32 v20, v20, v21
	v_add_f32_e32 v21, v22, v23
	v_add_f32_e32 v20, v20, v21
	v_lshlrev_b32_e32 v21, 2, v28
	ds_bpermute_b32 v21, v21, v20
	s_and_saveexec_b64 s[10:11], s[4:5]
	s_cbranch_execz .LBB0_1747
	s_waitcnt lgkmcnt(0)
	v_add_f32_e32 v20, v20, v21
	v_fmamk_f32 v20, v20, 0x3a800000, v18
	v_rsq_f32_e32 v20, v20
	v_add_u32_e32 v21, s26, v17
	ds_write_b32 v21, v20 offset:14336
	s_branch .LBB0_1747
